# phase B: filter item tail rewritten with 16B coalesced stores, ctx norm loop de-laddered (gain vectors hoisted), latent-row split 7/10 between 3-item and 2-item filter blocks
# speedup vs baseline: 1.0558x; 1.0095x over previous
.LBB0_150:
	s_mul_i32 s0, s60, 7
	s_mul_i32 s6, s60, 10
	s_add_i32 s6, s6, 0xffffff40
	s_cmp_lt_u32 s60, 64
	s_cselect_b32 s0, s0, s6
	s_cselect_b32 s6, 7, 10
	s_add_i32 s6, s0, s6
	s_cmp_ge_i32 s0, s6
	s_cbranch_scc1 .LBB0_159
	v_lshlrev_b32_e32 v68, 2, v144
	v_mov_b32_e32 v69, 0
	v_lshlrev_b32_e32 v70, 2, v85
	v_or_b32_e32 v2, 0x1000, v68
	v_mov_b32_e32 v3, v69
	v_add_u32_e32 v71, 0, v68
	v_or_b32_e32 v78, 0x400, v70
	v_lshl_add_u64 v[86:87], s[62:63], 0, v[68:69]
	v_lshl_add_u64 v[88:89], s[54:55], 0, v[68:69]
	v_lshl_add_u64 v[90:91], s[62:63], 0, v[2:3]
	v_lshl_add_u64 v[92:93], s[54:55], 0, v[2:3]
	v_or_b32_e32 v2, 0x2000, v68
	v_or_b32_e32 v68, 0x3000, v68
	v_or_b32_e32 v80, 0x500, v70
	v_lshl_add_u64 v[106:107], s[62:63], 0, v[68:69]
	v_lshl_add_u64 v[108:109], s[54:55], 0, v[68:69]
	v_lshlrev_b32_e32 v68, 2, v78
	v_or_b32_e32 v82, 0x600, v70
	s_mov_b64 s[8:9], 0x1800
	v_lshl_add_u64 v[116:117], s[64:65], 0, v[68:69]
	v_lshlrev_b32_e32 v68, 2, v80
	v_or_b32_e32 v84, 0x700, v70
	v_lshlrev_b32_e32 v0, 4, v85
	v_lshl_add_u64 v[94:95], v[86:87], 0, s[8:9]
	v_lshl_add_u64 v[96:97], v[88:89], 0, s[8:9]
	s_mov_b64 s[8:9], 0x2800
	v_mov_b32_e32 v1, v69
	v_lshl_add_u64 v[118:119], s[64:65], 0, v[68:69]
	v_lshlrev_b32_e32 v68, 2, v82
	v_add_u32_e32 v73, 0, v0
	v_lshl_add_u64 v[102:103], v[86:87], 0, s[8:9]
	v_lshl_add_u64 v[104:105], v[88:89], 0, s[8:9]
	s_mov_b64 s[8:9], 0x3800
	v_lshl_add_u64 v[114:115], s[64:65], 0, v[0:1]
	v_lshl_add_u64 v[120:121], s[64:65], 0, v[68:69]
	v_lshlrev_b32_e32 v68, 2, v84
	v_mbcnt_lo_u32_b32 v0, -1, 0
	v_or_b32_e32 v72, 0x100, v70
	v_or_b32_e32 v74, 0x200, v70
	v_or_b32_e32 v76, 0x300, v70
	v_lshl_add_u64 v[98:99], s[62:63], 0, v[2:3]
	v_lshl_add_u64 v[100:101], s[54:55], 0, v[2:3]
	v_lshl_add_u64 v[110:111], v[86:87], 0, s[8:9]
	v_lshl_add_u64 v[112:113], v[88:89], 0, s[8:9]
	v_lshl_add_u64 v[122:123], s[64:65], 0, v[68:69]
	s_mov_b32 s2, -1
	v_mov_b32_e32 v124, 0x358637bd
	s_mov_b32 s8, 0x3a000000
	s_mov_b32 s1, 0x800000
	s_mov_b64 s[10:11], 0x10000
	s_mov_b64 s[12:13], 0x8000
	v_mov_b32_e32 v75, 0xc000
	v_mbcnt_hi_u32_b32 v77, -1, v0
	global_load_dwordx4 v[180:183], v[114:115], off
	global_load_dwordx4 v[184:187], v[114:115], off offset:1024
	global_load_dwordx4 v[188:191], v[114:115], off offset:2048
	global_load_dwordx4 v[192:195], v[114:115], off offset:3072
	global_load_dwordx4 v[196:199], v[116:117], off
	global_load_dwordx4 v[200:203], v[118:119], off
	global_load_dwordx4 v[204:207], v[120:121], off
	global_load_dwordx4 v[208:211], v[122:123], off
	s_branch .LBB0_153

.LBB0_192:
	s_or_b64 exec, exec, s[10:11]
	v_lshlrev_b32_e32 v0, 3, v144
	v_sub_u32_e32 v1, 0x800, v0
	v_add_u32_e32 v2, 0xfffff800, v0
	v_cmp_gt_u32_e32 vcc, 0x100, v144
	v_lshlrev_b32_e32 v1, 5, v1
	v_lshlrev_b32_e32 v2, 5, v2
	v_add_u32_e32 v2, 16, v2
	v_mov_b32_e32 v4, 32
	s_movk_i32 s14, 0x100
	v_mov_b32_e32 v3, 0xffffffe0
	v_cmp_eq_u32_e64 s[10:11], s14, v144
	v_cmp_eq_u32_e64 s[12:13], 0, v144
	v_cndmask_b32_e32 v5, v2, v1, vcc
	v_cndmask_b32_e32 v4, v4, v3, vcc
	v_mov_b32_e32 v13, 0x10900
	v_lshlrev_b32_e32 v18, 4, v144
	v_add_u32_e32 v6, v5, v4
	v_add_u32_e32 v7, v6, v4
	v_add_u32_e32 v8, v7, v4
	v_add_u32_e32 v9, v8, v4
	v_add_u32_e32 v10, v9, v4
	v_add_u32_e32 v11, v10, v4
	v_add_u32_e32 v12, v11, v4
	v_cndmask_b32_e64 v5, v5, 0, s[10:11]
	ds_read_b128 v[14:17], v13
	ds_read_b128 v[80:83], v5
	ds_read_b128 v[84:87], v6
	ds_read_b128 v[88:91], v7
	ds_read_b128 v[92:95], v8
	ds_read_b128 v[96:99], v9
	ds_read_b128 v[100:103], v10
	ds_read_b128 v[104:107], v11
	ds_read_b128 v[108:111], v12
	s_waitcnt lgkmcnt(0)
	v_mul_f32_e32 v20, v80, v14
	v_mul_f32_e32 v21, v84, v14
	v_mul_f32_e32 v22, v88, v14
	v_mul_f32_e32 v23, v92, v14
	v_mul_f32_e32 v24, v96, v14
	v_mul_f32_e32 v25, v100, v14
	v_mul_f32_e32 v26, v104, v14
	v_mul_f32_e32 v27, v108, v14
	v_cndmask_b32_e64 v20, v20, 0, s[12:13]
	v_cvt_pk_bf16_f32 v0, v20, v21
	v_cvt_pk_bf16_f32 v1, v22, v23
	v_cvt_pk_bf16_f32 v2, v24, v25
	v_cvt_pk_bf16_f32 v3, v26, v27
	global_store_dwordx4 v18, v[0:3], s[72:73]
	v_mul_f32_e32 v20, v81, v15
	v_mul_f32_e32 v21, v85, v15
	v_mul_f32_e32 v22, v89, v15
	v_mul_f32_e32 v23, v93, v15
	v_mul_f32_e32 v24, v97, v15
	v_mul_f32_e32 v25, v101, v15
	v_mul_f32_e32 v26, v105, v15
	v_mul_f32_e32 v27, v109, v15
	v_cndmask_b32_e64 v20, v20, 0, s[12:13]
	v_cvt_pk_bf16_f32 v0, v20, v21
	v_cvt_pk_bf16_f32 v1, v22, v23
	v_cvt_pk_bf16_f32 v2, v24, v25
	v_cvt_pk_bf16_f32 v3, v26, v27
	s_add_u32 s14, s72, 0x2000
	s_addc_u32 s15, s73, 0
	global_store_dwordx4 v18, v[0:3], s[14:15]
	v_mul_f32_e32 v20, v82, v16
	v_mul_f32_e32 v21, v86, v16
	v_mul_f32_e32 v22, v90, v16
	v_mul_f32_e32 v23, v94, v16
	v_mul_f32_e32 v24, v98, v16
	v_mul_f32_e32 v25, v102, v16
	v_mul_f32_e32 v26, v106, v16
	v_mul_f32_e32 v27, v110, v16
	v_cndmask_b32_e64 v20, v20, 0, s[12:13]
	v_cvt_pk_bf16_f32 v0, v20, v21
	v_cvt_pk_bf16_f32 v1, v22, v23
	v_cvt_pk_bf16_f32 v2, v24, v25
	v_cvt_pk_bf16_f32 v3, v26, v27
	s_add_u32 s14, s72, 0x4000
	s_addc_u32 s15, s73, 0
	global_store_dwordx4 v18, v[0:3], s[14:15]
	v_mul_f32_e32 v20, v83, v17
	v_mul_f32_e32 v21, v87, v17
	v_mul_f32_e32 v22, v91, v17
	v_mul_f32_e32 v23, v95, v17
	v_mul_f32_e32 v24, v99, v17
	v_mul_f32_e32 v25, v103, v17
	v_mul_f32_e32 v26, v107, v17
	v_mul_f32_e32 v27, v111, v17
	v_cndmask_b32_e64 v20, v20, 0, s[12:13]
	v_cvt_pk_bf16_f32 v0, v20, v21
	v_cvt_pk_bf16_f32 v1, v22, v23
	v_cvt_pk_bf16_f32 v2, v24, v25
	v_cvt_pk_bf16_f32 v3, v26, v27
	s_add_u32 s14, s72, 0x6000
	s_addc_u32 s15, s73, 0
	global_store_dwordx4 v18, v[0:3], s[14:15]
	s_mov_b64 s[74:75], 0
	s_branch .LBB0_161

.LBB0_227:
	s_and_b64 vcc, exec, s[6:7]
	s_cbranch_vccz .LBB0_248
	v_lshlrev_b32_e32 v16, 2, v144
	v_mov_b32_e32 v17, 0
	s_waitcnt vmcnt(0)
	v_lshl_add_u64 v[0:1], s[54:55], 0, v[16:17]
	v_add_co_u32_e32 v4, vcc, 0x60000, v0
	s_mov_b32 s0, 0x60000
	s_nop 0
	v_addc_co_u32_e32 v5, vcc, 0, v1, vcc
	v_add_co_u32_e32 v6, vcc, 0xcc000, v0
	s_mov_b32 s1, 0xcc000
	s_nop 0
	v_addc_co_u32_e32 v7, vcc, 0, v1, vcc
	v_add_co_u32_e32 v8, vcc, 0x138000, v0
	s_mov_b32 s2, 0x138000
	s_nop 0
	v_addc_co_u32_e32 v9, vcc, 0, v1, vcc
	v_add_co_u32_e32 v10, vcc, 0x1a4000, v0
	s_mov_b32 s6, 0x1a4000
	s_nop 0
	v_addc_co_u32_e32 v11, vcc, 0, v1, vcc
	v_add_co_u32_e32 v12, vcc, 0x210000, v0
	s_mov_b32 s7, 0x210000
	s_nop 0
	v_addc_co_u32_e32 v13, vcc, 0, v1, vcc
	v_add_co_u32_e32 v14, vcc, 0x27c000, v0
	s_mov_b32 s8, 0x27c000
	s_nop 0
	v_addc_co_u32_e32 v15, vcc, 0, v1, vcc
	v_add_co_u32_e32 v18, vcc, 0x2e8000, v0
	s_mov_b32 s9, 0x2e8000
	s_nop 0
	v_addc_co_u32_e32 v19, vcc, 0, v1, vcc
	v_add_co_u32_e32 v20, vcc, 0x354000, v0
	s_mov_b32 s10, 0x354000
	s_nop 0
	v_addc_co_u32_e32 v21, vcc, 0, v1, vcc
	global_load_dword v26, v[4:5], off
	global_load_dword v27, v[6:7], off
	global_load_dword v28, v[8:9], off
	global_load_dword v29, v[10:11], off
	global_load_dword v30, v[10:11], off offset:2048
	global_load_dword v31, v[8:9], off offset:2048
	global_load_dword v32, v[6:7], off offset:2048
	global_load_dword v33, v[4:5], off offset:2048
	global_load_dword v34, v[12:13], off
	global_load_dword v35, v[14:15], off
	global_load_dword v36, v[18:19], off
	global_load_dword v37, v[20:21], off
	global_load_dword v38, v[20:21], off offset:2048
	global_load_dword v39, v[18:19], off offset:2048
	global_load_dword v40, v[14:15], off offset:2048
	global_load_dword v41, v[12:13], off offset:2048
	v_or_b32_e32 v4, 0x1000, v16
	v_mov_b32_e32 v5, v17
	v_lshl_add_u64 v[6:7], s[54:55], 0, v[4:5]
	v_add_co_u32_e32 v8, vcc, s0, v6
	v_lshl_add_u64 v[2:3], s[62:63], 0, v[16:17]
	s_nop 0
	v_addc_co_u32_e32 v9, vcc, 0, v7, vcc
	v_add_co_u32_e32 v10, vcc, s1, v6
	s_movk_i32 s11, 0x1000
	s_nop 0
	v_addc_co_u32_e32 v11, vcc, 0, v7, vcc
	v_add_co_u32_e32 v12, vcc, s2, v6
	s_and_b32 s12, s3, 7
	s_nop 0
	v_addc_co_u32_e32 v13, vcc, 0, v7, vcc
	v_add_co_u32_e32 v14, vcc, s6, v6
	s_movk_i32 s13, 0xf000
	s_nop 0
	v_addc_co_u32_e32 v15, vcc, 0, v7, vcc
	v_add_co_u32_e32 v18, vcc, s7, v6
	s_mov_b32 s14, 0x5e01000
	s_nop 0
	v_addc_co_u32_e32 v19, vcc, 0, v7, vcc
	v_add_co_u32_e32 v20, vcc, s8, v6
	s_nop 1
	v_addc_co_u32_e32 v21, vcc, 0, v7, vcc
	v_add_co_u32_e32 v22, vcc, s9, v6
	s_nop 1
	v_addc_co_u32_e32 v23, vcc, 0, v7, vcc
	v_add_co_u32_e32 v6, vcc, s10, v6
	s_nop 1
	v_addc_co_u32_e32 v7, vcc, 0, v7, vcc
	global_load_dword v42, v[8:9], off
	global_load_dword v43, v[10:11], off
	global_load_dword v44, v[12:13], off
	global_load_dword v45, v[14:15], off
	global_load_dword v46, v[18:19], off
	global_load_dword v47, v[20:21], off
	global_load_dword v48, v[22:23], off
	global_load_dword v49, v[6:7], off
	v_add_co_u32_e32 v6, vcc, s11, v2
	s_mov_b32 s11, 0x61000
	s_nop 0
	v_addc_co_u32_e32 v7, vcc, 0, v3, vcc
	global_load_dword v50, v[6:7], off offset:2048
	v_add_co_u32_e32 v6, vcc, s11, v0
	s_mov_b32 s11, 0xcd000
	s_nop 0
	v_addc_co_u32_e32 v7, vcc, 0, v1, vcc
	v_add_co_u32_e32 v8, vcc, s11, v0
	s_mov_b32 s11, 0x139000
	s_nop 0
	v_addc_co_u32_e32 v9, vcc, 0, v1, vcc
	v_add_co_u32_e32 v10, vcc, s11, v0
	s_mov_b32 s11, 0x1a5000
	s_nop 0
	v_addc_co_u32_e32 v11, vcc, 0, v1, vcc
	v_add_co_u32_e32 v12, vcc, s11, v0
	s_mov_b32 s11, 0x211000
	s_nop 0
	v_addc_co_u32_e32 v13, vcc, 0, v1, vcc
	v_add_co_u32_e32 v14, vcc, s11, v0
	s_mov_b32 s11, 0x27d000
	s_nop 0
	v_addc_co_u32_e32 v15, vcc, 0, v1, vcc
	v_add_co_u32_e32 v18, vcc, s11, v0
	s_mov_b32 s11, 0x2e9000
	s_nop 0
	v_addc_co_u32_e32 v19, vcc, 0, v1, vcc
	v_add_co_u32_e32 v20, vcc, s11, v0
	s_mov_b32 s11, 0x355000
	s_nop 0
	v_addc_co_u32_e32 v21, vcc, 0, v1, vcc
	v_add_co_u32_e32 v22, vcc, s11, v0
	s_movk_i32 s11, 0x2000
	s_nop 0
	v_addc_co_u32_e32 v23, vcc, 0, v1, vcc
	global_load_dword v51, v[6:7], off offset:2048
	global_load_dword v52, v[8:9], off offset:2048
	global_load_dword v53, v[10:11], off offset:2048
	global_load_dword v54, v[12:13], off offset:2048
	global_load_dword v55, v[14:15], off offset:2048
	global_load_dword v56, v[18:19], off offset:2048
	global_load_dword v57, v[20:21], off offset:2048
	global_load_dword v58, v[22:23], off offset:2048
	v_or_b32_e32 v6, 0x2000, v16
	v_mov_b32_e32 v7, v17
	v_lshl_add_u64 v[8:9], s[54:55], 0, v[6:7]
	v_add_co_u32_e32 v10, vcc, s0, v8
	s_nop 1
	v_addc_co_u32_e32 v11, vcc, 0, v9, vcc
	v_add_co_u32_e32 v12, vcc, s1, v8
	s_nop 1
	v_addc_co_u32_e32 v13, vcc, 0, v9, vcc
	v_add_co_u32_e32 v14, vcc, s2, v8
	s_nop 1
	v_addc_co_u32_e32 v15, vcc, 0, v9, vcc
	v_add_co_u32_e32 v18, vcc, s6, v8
	s_nop 1
	v_addc_co_u32_e32 v19, vcc, 0, v9, vcc
	v_add_co_u32_e32 v20, vcc, s7, v8
	s_nop 1
	v_addc_co_u32_e32 v21, vcc, 0, v9, vcc
	v_add_co_u32_e32 v22, vcc, s8, v8
	s_nop 1
	v_addc_co_u32_e32 v23, vcc, 0, v9, vcc
	v_add_co_u32_e32 v24, vcc, s9, v8
	s_nop 1
	v_addc_co_u32_e32 v25, vcc, 0, v9, vcc
	v_add_co_u32_e32 v8, vcc, s10, v8
	s_nop 1
	v_addc_co_u32_e32 v9, vcc, 0, v9, vcc
	global_load_dword v59, v[10:11], off
	global_load_dword v60, v[12:13], off
	global_load_dword v61, v[14:15], off
	global_load_dword v62, v[18:19], off
	global_load_dword v63, v[20:21], off
	global_load_dword v64, v[22:23], off
	global_load_dword v65, v[24:25], off
	global_load_dword v66, v[8:9], off
	v_add_co_u32_e32 v8, vcc, s11, v2
	s_mov_b32 s11, 0x62000
	s_nop 0
	v_addc_co_u32_e32 v9, vcc, 0, v3, vcc
	global_load_dword v67, v[8:9], off offset:2048
	v_add_co_u32_e32 v8, vcc, s11, v0
	s_mov_b32 s11, 0xce000
	s_nop 0
	v_addc_co_u32_e32 v9, vcc, 0, v1, vcc
	v_add_co_u32_e32 v10, vcc, s11, v0
	s_mov_b32 s11, 0x13a000
	s_nop 0
	v_addc_co_u32_e32 v11, vcc, 0, v1, vcc
	v_add_co_u32_e32 v12, vcc, s11, v0
	s_mov_b32 s11, 0x1a6000
	s_nop 0
	v_addc_co_u32_e32 v13, vcc, 0, v1, vcc
	v_add_co_u32_e32 v14, vcc, s11, v0
	s_mov_b32 s11, 0x212000
	s_nop 0
	v_addc_co_u32_e32 v15, vcc, 0, v1, vcc
	v_add_co_u32_e32 v18, vcc, s11, v0
	s_mov_b32 s11, 0x27e000
	s_nop 0
	v_addc_co_u32_e32 v19, vcc, 0, v1, vcc
	v_add_co_u32_e32 v20, vcc, s11, v0
	s_mov_b32 s11, 0x2ea000
	s_nop 0
	v_addc_co_u32_e32 v21, vcc, 0, v1, vcc
	v_add_co_u32_e32 v22, vcc, s11, v0
	s_mov_b32 s11, 0x356000
	s_nop 0
	v_addc_co_u32_e32 v23, vcc, 0, v1, vcc
	v_add_co_u32_e32 v24, vcc, s11, v0
	s_movk_i32 s11, 0x3000
	s_nop 0
	v_addc_co_u32_e32 v25, vcc, 0, v1, vcc
	global_load_dword v68, v[8:9], off offset:2048
	global_load_dword v69, v[10:11], off offset:2048
	global_load_dword v70, v[12:13], off offset:2048
	global_load_dword v71, v[14:15], off offset:2048
	global_load_dword v72, v[18:19], off offset:2048
	global_load_dword v73, v[20:21], off offset:2048
	s_nop 0
	global_load_dword v22, v[22:23], off offset:2048
	s_nop 0
	global_load_dword v23, v[24:25], off offset:2048
	v_or_b32_e32 v8, 0x3000, v16
	v_mov_b32_e32 v9, v17
	global_load_dword v24, v16, s[62:63]
	global_load_dword v25, v16, s[62:63] offset:2048
	global_load_dword v74, v4, s[62:63]
	global_load_dword v75, v6, s[62:63]
	global_load_dword v76, v8, s[62:63]
	v_lshl_add_u64 v[4:5], s[54:55], 0, v[8:9]
	v_add_co_u32_e32 v6, vcc, s0, v4
	s_mov_b32 s0, 0x63000
	s_nop 0
	v_addc_co_u32_e32 v7, vcc, 0, v5, vcc
	v_add_co_u32_e32 v8, vcc, s1, v4
	s_lshl_b32 s1, s3, 3
	s_nop 0
	v_addc_co_u32_e32 v9, vcc, 0, v5, vcc
	v_add_co_u32_e32 v10, vcc, s2, v4
	s_andn2_b32 s1, s1, 63
	s_nop 0
	v_addc_co_u32_e32 v11, vcc, 0, v5, vcc
	v_add_co_u32_e32 v12, vcc, s6, v4
	s_movk_i32 s2, 0xe000
	s_nop 0
	v_addc_co_u32_e32 v13, vcc, 0, v5, vcc
	v_add_co_u32_e32 v14, vcc, s7, v4
	s_mov_b64 s[6:7], 0
	s_nop 0
	v_addc_co_u32_e32 v15, vcc, 0, v5, vcc
	v_add_co_u32_e32 v18, vcc, s8, v4
	s_nop 1
	v_addc_co_u32_e32 v19, vcc, 0, v5, vcc
	v_add_co_u32_e32 v20, vcc, s9, v4
	s_mov_b64 s[8:9], 0x4000
	s_nop 0
	v_addc_co_u32_e32 v21, vcc, 0, v5, vcc
	v_add_co_u32_e32 v4, vcc, s10, v4
	s_mov_b32 s10, 0x800000
	s_nop 0
	v_addc_co_u32_e32 v5, vcc, 0, v5, vcc
	v_add_co_u32_e32 v2, vcc, s11, v2
	global_load_dword v77, v[6:7], off
	global_load_dword v78, v[8:9], off
	global_load_dword v79, v[10:11], off
	global_load_dword v80, v[12:13], off
	global_load_dword v81, v[14:15], off
	s_nop 0
	global_load_dword v18, v[18:19], off
	s_nop 0
	global_load_dword v19, v[20:21], off
	s_nop 0
	global_load_dword v20, v[4:5], off
	v_addc_co_u32_e32 v3, vcc, 0, v3, vcc
	global_load_dword v21, v[2:3], off offset:2048
	v_add_co_u32_e32 v2, vcc, s0, v0
	s_mov_b32 s0, 0xcf000
	s_nop 0
	v_addc_co_u32_e32 v3, vcc, 0, v1, vcc
	v_add_co_u32_e32 v4, vcc, s0, v0
	s_mov_b32 s0, 0x13b000
	s_nop 0
	v_addc_co_u32_e32 v5, vcc, 0, v1, vcc
	v_add_co_u32_e32 v6, vcc, s0, v0
	s_mov_b32 s0, 0x1a7000
	s_nop 0
	v_addc_co_u32_e32 v7, vcc, 0, v1, vcc
	v_add_co_u32_e32 v8, vcc, s0, v0
	s_mov_b32 s0, 0x213000
	s_nop 0
	v_addc_co_u32_e32 v9, vcc, 0, v1, vcc
	v_add_co_u32_e32 v10, vcc, s0, v0
	s_mov_b32 s0, 0x27f000
	s_nop 0
	v_addc_co_u32_e32 v11, vcc, 0, v1, vcc
	v_add_co_u32_e32 v12, vcc, s0, v0
	s_mov_b32 s0, 0x2eb000
	s_nop 0
	v_addc_co_u32_e32 v13, vcc, 0, v1, vcc
	v_add_co_u32_e32 v14, vcc, s0, v0
	s_mov_b32 s0, 0x357000
	s_nop 0
	v_addc_co_u32_e32 v15, vcc, 0, v1, vcc
	v_add_co_u32_e32 v0, vcc, s0, v0
	s_lshl_b32 s0, s12, 8
	s_nop 0
	v_addc_co_u32_e32 v1, vcc, 0, v1, vcc
	global_load_dword v2, v[2:3], off offset:2048
	s_nop 0
	global_load_dword v3, v[4:5], off offset:2048
	s_nop 0
	global_load_dword v4, v[6:7], off offset:2048
	global_load_dword v5, v[8:9], off offset:2048
	s_nop 0
	global_load_dword v6, v[10:11], off offset:2048
	global_load_dword v7, v[12:13], off offset:2048
	global_load_dword v8, v[14:15], off offset:2048
	s_nop 0
	global_load_dword v0, v[0:1], off offset:2048
	s_waitcnt vmcnt(21)
	v_add_f32_e32 v1, v24, v26
	s_waitcnt vmcnt(20)
	v_add_f32_e32 v10, v25, v33
	v_add_f32_e32 v1, v1, v27
	v_add_f32_e32 v10, v10, v32
	v_add_f32_e32 v1, v1, v28
	v_add_f32_e32 v10, v10, v31
	v_add_f32_e32 v1, v1, v29
	v_add_f32_e32 v10, v10, v30
	v_add_f32_e32 v1, v1, v34
	v_add_f32_e32 v10, v10, v41
	v_add_f32_e32 v1, v1, v35
	v_add_f32_e32 v10, v10, v40
	v_add_f32_e32 v1, v1, v36
	v_add_f32_e32 v10, v10, v39
	v_add_f32_e32 v1, v1, v37
	v_add_u32_e32 v9, 0, v16
	v_add_f32_e32 v10, v10, v38
	ds_write2st64_b32 v9, v1, v10 offset1:8
	s_waitcnt vmcnt(19)
	v_add_f32_e32 v1, v74, v42
	v_add_f32_e32 v10, v50, v51
	v_add_f32_e32 v1, v1, v43
	v_add_f32_e32 v10, v10, v52
	v_add_f32_e32 v1, v1, v44
	v_add_f32_e32 v10, v10, v53
	v_add_f32_e32 v1, v1, v45
	v_add_f32_e32 v10, v10, v54
	v_add_f32_e32 v1, v1, v46
	v_add_f32_e32 v10, v10, v55
	v_add_f32_e32 v1, v1, v47
	v_add_f32_e32 v10, v10, v56
	v_add_f32_e32 v1, v1, v48
	v_add_f32_e32 v10, v10, v57
	v_add_f32_e32 v1, v1, v49
	v_add_f32_e32 v10, v10, v58
	ds_write2st64_b32 v9, v1, v10 offset0:16 offset1:24
	s_waitcnt vmcnt(18)
	v_add_f32_e32 v1, v75, v59
	v_add_f32_e32 v10, v67, v68
	v_add_f32_e32 v1, v1, v60
	v_add_f32_e32 v10, v10, v69
	v_add_f32_e32 v1, v1, v61
	v_add_f32_e32 v10, v10, v70
	v_add_f32_e32 v1, v1, v62
	v_add_f32_e32 v10, v10, v71
	v_add_f32_e32 v1, v1, v63
	v_add_f32_e32 v10, v10, v72
	v_add_f32_e32 v1, v1, v64
	v_add_f32_e32 v10, v10, v73
	v_add_f32_e32 v1, v1, v65
	v_add_f32_e32 v10, v10, v22
	v_add_f32_e32 v1, v1, v66
	v_add_f32_e32 v10, v10, v23
	ds_write2st64_b32 v9, v1, v10 offset0:32 offset1:40
	s_waitcnt vmcnt(16)
	v_add_f32_e32 v1, v76, v77
	s_waitcnt vmcnt(15)
	v_add_f32_e32 v1, v1, v78
	s_waitcnt vmcnt(14)
	v_add_f32_e32 v1, v1, v79
	s_waitcnt vmcnt(13)
	v_add_f32_e32 v1, v1, v80
	s_waitcnt vmcnt(12)
	v_add_f32_e32 v1, v1, v81
	s_waitcnt vmcnt(11)
	v_add_f32_e32 v1, v1, v18
	s_waitcnt vmcnt(10)
	v_add_f32_e32 v1, v1, v19
	s_waitcnt vmcnt(9)
	v_add_f32_e32 v1, v1, v20
	s_add_i32 s0, s0, s1
	s_mov_b32 s11, 0x5e00000
	s_waitcnt vmcnt(7)
	v_add_f32_e32 v2, v21, v2
	s_waitcnt vmcnt(6)
	v_add_f32_e32 v2, v2, v3
	s_waitcnt vmcnt(5)
	v_add_f32_e32 v2, v2, v4
	s_waitcnt vmcnt(4)
	v_add_f32_e32 v2, v2, v5
	s_waitcnt vmcnt(3)
	v_add_f32_e32 v2, v2, v6
	s_waitcnt vmcnt(2)
	v_add_f32_e32 v2, v2, v7
	s_waitcnt vmcnt(1)
	v_add_f32_e32 v2, v2, v8
	s_waitcnt vmcnt(0)
	v_add_f32_e32 v0, v2, v0
	ds_write2st64_b32 v9, v1, v0 offset0:48 offset1:56
	v_mbcnt_lo_u32_b32 v1, -1, 0
	v_mbcnt_hi_u32_b32 v1, -1, v1
	v_and_b32_e32 v2, 64, v1
	v_add_u32_e32 v2, 64, v2
	v_xor_b32_e32 v3, 32, v1
	v_cmp_lt_i32_e32 vcc, v3, v2
	v_mov_b32_e32 v5, v17
	v_lshl_add_u32 v0, v125, 3, s0
	v_cndmask_b32_e32 v3, v1, v3, vcc
	v_lshlrev_b32_e32 v34, 2, v3
	v_xor_b32_e32 v3, 16, v1
	v_cmp_lt_i32_e32 vcc, v3, v2
	s_mov_b64 s[0:1], 0x3c00
	s_waitcnt lgkmcnt(0)
	v_cndmask_b32_e32 v3, v1, v3, vcc
	v_lshlrev_b32_e32 v35, 2, v3
	v_xor_b32_e32 v3, 8, v1
	v_cmp_lt_i32_e32 vcc, v3, v2
	s_barrier
	s_nop 0
	v_cndmask_b32_e32 v3, v1, v3, vcc
	v_lshlrev_b32_e32 v36, 2, v3
	v_xor_b32_e32 v3, 4, v1
	v_cmp_lt_i32_e32 vcc, v3, v2
	s_nop 1
	v_cndmask_b32_e32 v3, v1, v3, vcc
	v_lshlrev_b32_e32 v37, 2, v3
	v_xor_b32_e32 v3, 2, v1
	v_cmp_lt_i32_e32 vcc, v3, v2
	s_nop 1
	v_cndmask_b32_e32 v3, v1, v3, vcc
	v_lshlrev_b32_e32 v38, 2, v3
	v_xor_b32_e32 v3, 1, v1
	v_cmp_lt_i32_e32 vcc, v3, v2
	v_lshlrev_b32_e32 v2, 4, v85
	v_or_b32_e32 v4, 0x1000, v2
	v_cndmask_b32_e32 v1, v1, v3, vcc
	v_mov_b32_e32 v3, v17
	v_lshl_add_u64 v[20:21], s[64:65], 0, v[4:5]
	v_or_b32_e32 v4, 0x1400, v2
	v_add_u32_e32 v40, 0, v2
	v_lshl_add_u64 v[18:19], s[64:65], 0, v[2:3]
	v_lshl_add_u64 v[22:23], s[64:65], 0, v[4:5]
	v_or_b32_e32 v4, 0x1800, v2
	v_or_b32_e32 v2, 0x1c00, v2
	v_lshlrev_b32_e32 v39, 2, v1
	v_lshl_add_u64 v[26:27], s[64:65], 0, v[2:3]
	v_add_u32_e32 v2, 0x4000, v0
	v_ashrrev_i32_e32 v1, 31, v0
	v_ashrrev_i32_e32 v3, 31, v2
	v_lshlrev_b64 v[0:1], 13, v[0:1]
	v_lshlrev_b64 v[2:3], 12, v[2:3]
	v_lshl_or_b32 v0, v85, 4, v0
	v_lshl_or_b32 v2, v85, 3, v2
	v_lshl_add_u64 v[0:1], s[56:57], 0, v[0:1]
	v_lshl_add_u64 v[24:25], s[64:65], 0, v[4:5]
	v_lshl_add_u64 v[28:29], s[22:23], 0, v[2:3]
	v_lshl_add_u64 v[30:31], v[0:1], 0, s[0:1]
	v_mov_b32_e32 v17, 0x358637bd
	global_load_dwordx4 v[180:183], v[18:19], off
	global_load_dwordx4 v[184:187], v[18:19], off offset:1024
	global_load_dwordx4 v[188:191], v[18:19], off offset:2048
	global_load_dwordx4 v[192:195], v[18:19], off offset:3072
	global_load_dwordx4 v[196:199], v[20:21], off
	global_load_dwordx4 v[200:203], v[22:23], off
	global_load_dwordx4 v[204:207], v[24:25], off
	global_load_dwordx4 v[208:211], v[26:27], off
.LBB0_229:
	v_add_co_u32_e32 v14, vcc, 0xffffd000, v30
	v_add_co_u32_e64 v0, s[0:1], s2, v30
	s_nop 0
	v_addc_co_u32_e32 v15, vcc, -1, v31, vcc
	v_addc_co_u32_e64 v1, s[0:1], -1, v31, s[0:1]
	global_load_dwordx4 v[10:13], v[18:19], off
	ds_read_b128 v[42:45], v40 offset:8192
	ds_read_b128 v[46:49], v40
	global_load_dwordx4 v[50:53], v[0:1], off offset:-3072 nt
	global_load_dwordx4 v[54:57], v[0:1], off offset:-2048 nt
	global_load_dwordx4 v[4:7], v[0:1], off offset:-1024 nt
	s_nop 0
	global_load_dwordx4 v[0:3], v[0:1], off nt
	s_nop 0
	global_load_dwordx4 v[58:61], v[14:15], off offset:-3072 nt
	global_load_dwordx4 v[62:65], v[14:15], off offset:-2048 nt
	global_load_dwordx4 v[66:69], v[14:15], off offset:-1024 nt
	global_load_dwordx4 v[70:73], v[14:15], off nt
	s_waitcnt lgkmcnt(1)
	v_pk_add_f32 v[14:15], v[42:43], 1.0 op_sel_hi:[1,0]
	v_pk_add_f32 v[42:43], v[44:45], 1.0 op_sel_hi:[1,0]
	v_lshl_add_u64 v[32:33], v[28:29], 0, s[6:7]
	v_add_co_u32_e32 v8, vcc, s11, v32
	s_add_u32 s6, s6, 0x2000
	s_nop 0
	v_addc_co_u32_e32 v9, vcc, 0, v33, vcc
	v_add_co_u32_e32 v32, vcc, s14, v32
	s_addc_u32 s7, s7, 0
	s_nop 0
	v_addc_co_u32_e32 v33, vcc, 0, v33, vcc
	s_cmpk_eq_u32 s6, 0x8000
	s_waitcnt vmcnt(3)
	v_mul_f32_e32 v41, v59, v59
	s_waitcnt vmcnt(2)
	v_mul_f32_e32 v88, v63, v63
	s_waitcnt vmcnt(1)
	v_mul_f32_e32 v89, v67, v67
	v_fmac_f32_e32 v41, v58, v58
	v_fmac_f32_e32 v88, v62, v62
	v_mov_b32_e32 v74, v51
	v_mov_b32_e32 v75, v55
	s_waitcnt vmcnt(0)
	v_mul_f32_e32 v90, v71, v71
	v_fmac_f32_e32 v89, v66, v66
	v_fmac_f32_e32 v41, v60, v60
	v_fmac_f32_e32 v88, v64, v64
	v_mov_b32_e32 v44, v50
	v_mov_b32_e32 v45, v54
	v_pk_mul_f32 v[74:75], v[74:75], v[74:75]
	v_fmac_f32_e32 v90, v70, v70
	v_fmac_f32_e32 v89, v68, v68
	v_fmac_f32_e32 v41, v61, v61
	v_fmac_f32_e32 v88, v65, v65
	v_mov_b32_e32 v76, v52
	v_mov_b32_e32 v77, v56
	v_mov_b32_e32 v82, v5
	v_mov_b32_e32 v83, v1
	v_pk_fma_f32 v[44:45], v[44:45], v[44:45], v[74:75]
	v_fmac_f32_e32 v90, v72, v72
	v_fmac_f32_e32 v89, v69, v69
	v_add_f32_e32 v41, v41, v88
	v_mov_b32_e32 v78, v53
	v_mov_b32_e32 v79, v57
	v_mov_b32_e32 v80, v4
	v_mov_b32_e32 v81, v0
	v_pk_mul_f32 v[82:83], v[82:83], v[82:83]
	v_pk_fma_f32 v[44:45], v[76:77], v[76:77], v[44:45]
	v_fmac_f32_e32 v90, v73, v73
	v_add_f32_e32 v41, v41, v89
	v_mov_b32_e32 v84, v6
	v_mov_b32_e32 v85, v2
	v_pk_fma_f32 v[74:75], v[80:81], v[80:81], v[82:83]
	v_pk_fma_f32 v[44:45], v[78:79], v[78:79], v[44:45]
	v_add_f32_e32 v41, v41, v90
	v_mov_b32_e32 v86, v7
	v_mov_b32_e32 v87, v3
	v_pk_fma_f32 v[74:75], v[84:85], v[84:85], v[74:75]
	v_add_f32_e32 v41, v41, v44
	v_pk_fma_f32 v[74:75], v[86:87], v[86:87], v[74:75]
	v_add_f32_e32 v41, v41, v45
	v_add_f32_e32 v41, v41, v74
	v_add_f32_e32 v41, v41, v75
	ds_bpermute_b32 v44, v34, v41
	s_waitcnt lgkmcnt(0)
	v_add_f32_e32 v41, v41, v44
	ds_bpermute_b32 v44, v35, v41
	s_waitcnt lgkmcnt(0)
	v_add_f32_e32 v41, v41, v44
	ds_bpermute_b32 v44, v36, v41
	s_waitcnt lgkmcnt(0)
	v_add_f32_e32 v41, v41, v44
	ds_bpermute_b32 v44, v37, v41
	s_waitcnt lgkmcnt(0)
	v_add_f32_e32 v41, v41, v44
	ds_bpermute_b32 v44, v38, v41
	s_waitcnt lgkmcnt(0)
	v_add_f32_e32 v41, v41, v44
	ds_bpermute_b32 v44, v39, v41
	s_waitcnt lgkmcnt(0)
	v_add_f32_e32 v41, v41, v44
	v_fmamk_f32 v41, v41, 0x3a000000, v17
	v_mul_f32_e32 v44, 0x4b800000, v41
	v_cmp_gt_f32_e32 vcc, s10, v41
	s_nop 1
	v_cndmask_b32_e32 v41, v41, v44, vcc
	v_rsq_f32_e32 v41, v41
	s_nop 0
	v_mul_f32_e32 v44, 0x45800000, v41
	v_cndmask_b32_e32 v74, v41, v44, vcc
	v_pk_mul_f32 v[44:45], v[58:59], v[74:75] op_sel_hi:[1,0]
	v_pk_mul_f32 v[58:59], v[60:61], v[74:75] op_sel_hi:[1,0]
	v_pk_mul_f32 v[10:11], v[10:11], v[44:45]
	v_pk_mul_f32 v[12:13], v[12:13], v[58:59]
	v_pk_fma_f32 v[10:11], v[14:15], v[10:11], v[46:47]
	v_pk_fma_f32 v[12:13], v[42:43], v[12:13], v[48:49]
	v_cvt_pk_bf16_f32 v10, v10, v11
	v_cvt_pk_bf16_f32 v11, v12, v13
	global_store_dwordx2 v[32:33], v[10:11], off offset:-4096 sc1
	ds_read_b128 v[42:45], v40 offset:9216
	ds_read_b128 v[46:49], v40 offset:1024
	v_pk_mul_f32 v[60:61], v[62:63], v[74:75] op_sel_hi:[1, 0]
	v_pk_mul_f32 v[62:63], v[64:65], v[74:75] op_sel_hi:[1, 0]
	v_pk_mul_f32 v[64:65], v[66:67], v[74:75] op_sel_hi:[1, 0]
	s_waitcnt lgkmcnt(1)
	v_pk_add_f32 v[14:15], v[42:43], 1.0 op_sel_hi:[1, 0]
	v_pk_add_f32 v[42:43], v[44:45], 1.0 op_sel_hi:[1, 0]
	v_pk_mul_f32 v[66:67], v[68:69], v[74:75] op_sel_hi:[1, 0]
	v_pk_mul_f32 v[68:69], v[70:71], v[74:75] op_sel_hi:[1, 0]
	v_pk_mul_f32 v[70:71], v[72:73], v[74:75] op_sel_hi:[1, 0]
	v_pk_mul_f32 v[50:51], v[50:51], v[74:75] op_sel_hi:[1, 0]
	v_pk_mul_f32 v[52:53], v[52:53], v[74:75] op_sel_hi:[1, 0]
	v_pk_mul_f32 v[54:55], v[54:55], v[74:75] op_sel_hi:[1, 0]
	s_waitcnt vmcnt(1)
	v_pk_mul_f32 v[10:11], v[184:185], v[60:61]
	v_pk_mul_f32 v[12:13], v[186:187], v[62:63]
	s_waitcnt lgkmcnt(0)
	v_pk_fma_f32 v[10:11], v[14:15], v[10:11], v[46:47]
	v_pk_fma_f32 v[12:13], v[42:43], v[12:13], v[48:49]
	v_cvt_pk_bf16_f32 v10, v10, v11
	v_cvt_pk_bf16_f32 v11, v12, v13
	global_store_dwordx2 v[8:9], v[10:11], off offset:512 sc1
	ds_read_b128 v[42:45], v40 offset:10240
	ds_read_b128 v[46:49], v40 offset:2048
	s_waitcnt lgkmcnt(1)
	v_pk_add_f32 v[14:15], v[42:43], 1.0 op_sel_hi:[1, 0]
	v_pk_add_f32 v[42:43], v[44:45], 1.0 op_sel_hi:[1, 0]
	s_waitcnt vmcnt(2)
	v_pk_mul_f32 v[10:11], v[188:189], v[64:65]
	v_pk_mul_f32 v[12:13], v[190:191], v[66:67]
	s_waitcnt lgkmcnt(0)
	v_pk_fma_f32 v[10:11], v[14:15], v[10:11], v[46:47]
	v_pk_fma_f32 v[12:13], v[42:43], v[12:13], v[48:49]
	v_cvt_pk_bf16_f32 v10, v10, v11
	v_cvt_pk_bf16_f32 v11, v12, v13
	global_store_dwordx2 v[8:9], v[10:11], off offset:1024 sc1
	ds_read_b128 v[42:45], v40 offset:11264
	ds_read_b128 v[46:49], v40 offset:3072
	s_waitcnt lgkmcnt(1)
	v_pk_add_f32 v[14:15], v[42:43], 1.0 op_sel_hi:[1, 0]
	v_pk_add_f32 v[42:43], v[44:45], 1.0 op_sel_hi:[1, 0]
	s_waitcnt vmcnt(3)
	v_pk_mul_f32 v[10:11], v[68:69], v[192:193]
	v_pk_mul_f32 v[12:13], v[70:71], v[194:195]
	s_waitcnt lgkmcnt(0)
	v_pk_fma_f32 v[10:11], v[10:11], v[14:15], v[46:47]
	v_pk_fma_f32 v[12:13], v[12:13], v[42:43], v[48:49]
	v_cvt_pk_bf16_f32 v10, v10, v11
	v_cvt_pk_bf16_f32 v11, v12, v13
	global_store_dwordx2 v[8:9], v[10:11], off offset:1536 sc1
	ds_read_b128 v[42:45], v40 offset:12288
	ds_read_b128 v[46:49], v40 offset:4096
	s_waitcnt lgkmcnt(1)
	v_pk_add_f32 v[14:15], v[42:43], 1.0 op_sel_hi:[1, 0]
	v_pk_add_f32 v[42:43], v[44:45], 1.0 op_sel_hi:[1, 0]
	s_waitcnt vmcnt(4)
	v_pk_mul_f32 v[10:11], v[50:51], v[196:197]
	v_pk_mul_f32 v[12:13], v[52:53], v[198:199]
	s_waitcnt lgkmcnt(0)
	v_pk_fma_f32 v[10:11], v[10:11], v[14:15], v[46:47]
	v_pk_fma_f32 v[12:13], v[12:13], v[42:43], v[48:49]
	v_cvt_pk_bf16_f32 v10, v10, v11
	v_cvt_pk_bf16_f32 v11, v12, v13
	global_store_dwordx2 v[8:9], v[10:11], off offset:2048 sc1
	ds_read_b128 v[42:45], v40 offset:13312
	ds_read_b128 v[46:49], v40 offset:5120
	v_pk_mul_f32 v[14:15], v[56:57], v[74:75] op_sel_hi:[1, 0]
	s_waitcnt lgkmcnt(1)
	v_pk_add_f32 v[42:43], v[42:43], 1.0 op_sel_hi:[1, 0]
	v_pk_add_f32 v[44:45], v[44:45], 1.0 op_sel_hi:[1, 0]
	s_waitcnt vmcnt(5)
	v_pk_mul_f32 v[10:11], v[54:55], v[200:201]
	v_pk_mul_f32 v[12:13], v[14:15], v[202:203]
	s_waitcnt lgkmcnt(0)
	v_pk_fma_f32 v[10:11], v[10:11], v[42:43], v[46:47]
	v_pk_fma_f32 v[12:13], v[12:13], v[44:45], v[48:49]
	v_cvt_pk_bf16_f32 v10, v10, v11
	v_cvt_pk_bf16_f32 v11, v12, v13
	global_store_dwordx2 v[8:9], v[10:11], off offset:2560 sc1
	v_pk_mul_f32 v[14:15], v[4:5], v[74:75] op_sel_hi:[1, 0]
	v_pk_mul_f32 v[46:47], v[6:7], v[74:75] op_sel_hi:[1, 0]
	ds_read_b128 v[4:7], v40 offset:14336
	ds_read_b128 v[42:45], v40 offset:6144
	s_waitcnt lgkmcnt(1)
	v_pk_add_f32 v[4:5], v[4:5], 1.0 op_sel_hi:[1, 0]
	v_pk_add_f32 v[6:7], v[6:7], 1.0 op_sel_hi:[1, 0]
	s_waitcnt vmcnt(6)
	v_pk_mul_f32 v[10:11], v[14:15], v[204:205]
	v_pk_mul_f32 v[12:13], v[46:47], v[206:207]
	s_waitcnt lgkmcnt(0)
	v_pk_fma_f32 v[4:5], v[10:11], v[4:5], v[42:43]
	v_pk_fma_f32 v[6:7], v[12:13], v[6:7], v[44:45]
	v_cvt_pk_bf16_f32 v4, v4, v5
	v_cvt_pk_bf16_f32 v5, v6, v7
	global_store_dwordx2 v[8:9], v[4:5], off offset:3072 sc1
	v_pk_mul_f32 v[42:43], v[0:1], v[74:75] op_sel_hi:[1, 0]
	v_pk_mul_f32 v[44:45], v[2:3], v[74:75] op_sel_hi:[1, 0]
	ds_read_b128 v[0:3], v40 offset:15360
	ds_read_b128 v[10:13], v40 offset:7168
	v_add_co_u32_e32 v14, vcc, s13, v30
	s_waitcnt lgkmcnt(1)
	v_pk_add_f32 v[0:1], v[0:1], 1.0 op_sel_hi:[1, 0]
	v_pk_add_f32 v[2:3], v[2:3], 1.0 op_sel_hi:[1, 0]
	v_addc_co_u32_e32 v15, vcc, -1, v31, vcc
	s_waitcnt vmcnt(7)
	v_pk_mul_f32 v[4:5], v[42:43], v[208:209]
	v_pk_mul_f32 v[6:7], v[44:45], v[210:211]
	s_waitcnt lgkmcnt(0)
	v_pk_fma_f32 v[0:1], v[4:5], v[0:1], v[10:11]
	v_pk_fma_f32 v[2:3], v[6:7], v[2:3], v[12:13]
	v_cvt_pk_bf16_f32 v0, v0, v1
	v_cvt_pk_bf16_f32 v1, v2, v3
	global_load_dwordx4 v[42:45], v[14:15], off offset:-3072 nt
	global_load_dwordx4 v[46:49], v[14:15], off offset:-2048 nt
	global_load_dwordx4 v[50:53], v[14:15], off offset:-1024 nt
	global_load_dwordx4 v[54:57], v[30:31], off offset:-4096 nt
	s_nop 0
	global_load_dwordx4 v[12:15], v[30:31], off offset:-3072 nt
	global_store_dwordx2 v[8:9], v[0:1], off offset:3584 sc1
	global_load_dwordx4 v[8:11], v[30:31], off offset:-2048 nt
	global_load_dwordx4 v[4:7], v[30:31], off offset:-1024 nt
	global_load_dwordx4 v[0:3], v[30:31], off nt
	ds_read_b128 v[58:61], v40 offset:8192
	ds_read_b128 v[66:69], v40
	v_lshl_add_u64 v[30:31], v[30:31], 0, s[8:9]
	s_waitcnt lgkmcnt(1)
	v_pk_add_f32 v[58:59], v[58:59], 1.0 op_sel_hi:[1, 0]
	v_pk_add_f32 v[60:61], v[60:61], 1.0 op_sel_hi:[1, 0]
	s_waitcnt vmcnt(8)
	v_mul_f32_e32 v41, v43, v43
	s_waitcnt vmcnt(7)
	v_mul_f32_e32 v86, v47, v47
	s_waitcnt vmcnt(6)
	v_mul_f32_e32 v87, v51, v51
	v_fmac_f32_e32 v41, v42, v42
	v_fmac_f32_e32 v86, v46, v46
	s_waitcnt vmcnt(5)
	v_mul_f32_e32 v88, v55, v55
	s_waitcnt vmcnt(4)
	v_mov_b32_e32 v72, v13
	s_waitcnt vmcnt(2)
	v_mov_b32_e32 v73, v9
	v_fmac_f32_e32 v87, v50, v50
	v_fmac_f32_e32 v41, v44, v44
	v_fmac_f32_e32 v86, v48, v48
	v_mov_b32_e32 v70, v12
	v_mov_b32_e32 v71, v8
	v_fmac_f32_e32 v88, v54, v54
	v_pk_mul_f32 v[72:73], v[72:73], v[72:73]
	v_fmac_f32_e32 v87, v52, v52
	v_fmac_f32_e32 v41, v45, v45
	v_fmac_f32_e32 v86, v49, v49
	v_mov_b32_e32 v74, v14
	v_mov_b32_e32 v75, v10
	s_waitcnt vmcnt(1)
	v_mov_b32_e32 v80, v5
	s_waitcnt vmcnt(0)
	v_mov_b32_e32 v81, v1
	v_fmac_f32_e32 v88, v56, v56
	v_pk_fma_f32 v[70:71], v[70:71], v[70:71], v[72:73]
	v_fmac_f32_e32 v87, v53, v53
	v_add_f32_e32 v41, v41, v86
	v_mov_b32_e32 v76, v15
	v_mov_b32_e32 v77, v11
	v_mov_b32_e32 v78, v4
	v_mov_b32_e32 v79, v0
	v_pk_mul_f32 v[80:81], v[80:81], v[80:81]
	v_fmac_f32_e32 v88, v57, v57
	v_pk_fma_f32 v[70:71], v[74:75], v[74:75], v[70:71]
	v_add_f32_e32 v41, v41, v87
	v_mov_b32_e32 v82, v6
	v_mov_b32_e32 v83, v2
	v_pk_fma_f32 v[72:73], v[78:79], v[78:79], v[80:81]
	v_pk_fma_f32 v[70:71], v[76:77], v[76:77], v[70:71]
	v_add_f32_e32 v41, v41, v88
	v_mov_b32_e32 v84, v7
	v_mov_b32_e32 v85, v3
	v_pk_fma_f32 v[72:73], v[82:83], v[82:83], v[72:73]
	v_add_f32_e32 v41, v41, v70
	v_pk_fma_f32 v[72:73], v[84:85], v[84:85], v[72:73]
	v_add_f32_e32 v41, v41, v71
	v_add_f32_e32 v41, v41, v72
	v_add_f32_e32 v41, v41, v73
	ds_bpermute_b32 v70, v34, v41
	s_waitcnt lgkmcnt(0)
	v_add_f32_e32 v41, v41, v70
	ds_bpermute_b32 v70, v35, v41
	s_waitcnt lgkmcnt(0)
	v_add_f32_e32 v41, v41, v70
	ds_bpermute_b32 v70, v36, v41
	s_waitcnt lgkmcnt(0)
	v_add_f32_e32 v41, v41, v70
	ds_bpermute_b32 v70, v37, v41
	s_waitcnt lgkmcnt(0)
	v_add_f32_e32 v41, v41, v70
	ds_bpermute_b32 v70, v38, v41
	s_waitcnt lgkmcnt(0)
	v_add_f32_e32 v41, v41, v70
	ds_bpermute_b32 v70, v39, v41
	s_waitcnt lgkmcnt(0)
	v_add_f32_e32 v41, v41, v70
	v_fmamk_f32 v41, v41, 0x3a000000, v17
	v_mul_f32_e32 v70, 0x4b800000, v41
	v_cmp_gt_f32_e32 vcc, s10, v41
	s_nop 1
	v_cndmask_b32_e32 v41, v41, v70, vcc
	v_rsq_f32_e32 v41, v41
	s_nop 0
	v_mul_f32_e32 v70, 0x45800000, v41
	v_cndmask_b32_e32 v70, v41, v70, vcc
	v_pk_mul_f32 v[42:43], v[42:43], v[70:71] op_sel_hi:[1, 0]
	v_pk_mul_f32 v[44:45], v[44:45], v[70:71] op_sel_hi:[1, 0]
	s_waitcnt vmcnt(0)
	v_pk_mul_f32 v[42:43], v[180:181], v[42:43]
	v_pk_mul_f32 v[44:45], v[182:183], v[44:45]
	v_pk_fma_f32 v[42:43], v[58:59], v[42:43], v[66:67]
	v_pk_fma_f32 v[44:45], v[60:61], v[44:45], v[68:69]
	v_cvt_pk_bf16_f32 v42, v42, v43
	v_cvt_pk_bf16_f32 v43, v44, v45
	global_store_dwordx2 v[32:33], v[42:43], off sc1
	v_pk_mul_f32 v[62:63], v[46:47], v[70:71] op_sel_hi:[1, 0]
	v_pk_mul_f32 v[64:65], v[48:49], v[70:71] op_sel_hi:[1, 0]
	ds_read_b128 v[46:49], v40 offset:9216
	ds_read_b128 v[58:61], v40 offset:1024
	v_pk_mul_f32 v[54:55], v[54:55], v[70:71] op_sel_hi:[1, 0]
	v_pk_mul_f32 v[56:57], v[56:57], v[70:71] op_sel_hi:[1, 0]
	s_waitcnt lgkmcnt(1)
	v_pk_add_f32 v[46:47], v[46:47], 1.0 op_sel_hi:[1, 0]
	v_pk_add_f32 v[48:49], v[48:49], 1.0 op_sel_hi:[1, 0]
	s_waitcnt vmcnt(1)
	v_pk_mul_f32 v[42:43], v[184:185], v[62:63]
	v_pk_mul_f32 v[44:45], v[186:187], v[64:65]
	s_waitcnt lgkmcnt(0)
	v_pk_fma_f32 v[42:43], v[46:47], v[42:43], v[58:59]
	v_pk_fma_f32 v[44:45], v[48:49], v[44:45], v[60:61]
	v_cvt_pk_bf16_f32 v42, v42, v43
	v_cvt_pk_bf16_f32 v43, v44, v45
	global_store_dwordx2 v[32:33], v[42:43], off offset:512 sc1
	v_pk_mul_f32 v[58:59], v[50:51], v[70:71] op_sel_hi:[1, 0]
	v_pk_mul_f32 v[60:61], v[52:53], v[70:71] op_sel_hi:[1, 0]
	ds_read_b128 v[46:49], v40 offset:10240
	ds_read_b128 v[50:53], v40 offset:2048
	s_waitcnt lgkmcnt(1)
	v_pk_add_f32 v[46:47], v[46:47], 1.0 op_sel_hi:[1, 0]
	v_pk_add_f32 v[48:49], v[48:49], 1.0 op_sel_hi:[1, 0]
	s_waitcnt vmcnt(2)
	v_pk_mul_f32 v[42:43], v[188:189], v[58:59]
	v_pk_mul_f32 v[44:45], v[190:191], v[60:61]
	s_waitcnt lgkmcnt(0)
	v_pk_fma_f32 v[42:43], v[46:47], v[42:43], v[50:51]
	v_pk_fma_f32 v[44:45], v[48:49], v[44:45], v[52:53]
	v_cvt_pk_bf16_f32 v42, v42, v43
	v_cvt_pk_bf16_f32 v43, v44, v45
	global_store_dwordx2 v[32:33], v[42:43], off offset:1024 sc1
	ds_read_b128 v[46:49], v40 offset:11264
	ds_read_b128 v[50:53], v40 offset:3072
	s_waitcnt lgkmcnt(1)
	v_pk_add_f32 v[46:47], v[46:47], 1.0 op_sel_hi:[1, 0]
	v_pk_add_f32 v[48:49], v[48:49], 1.0 op_sel_hi:[1, 0]
	s_waitcnt vmcnt(3)
	v_pk_mul_f32 v[42:43], v[54:55], v[192:193]
	v_pk_mul_f32 v[44:45], v[56:57], v[194:195]
	s_waitcnt lgkmcnt(0)
	v_pk_fma_f32 v[42:43], v[42:43], v[46:47], v[50:51]
	v_pk_fma_f32 v[44:45], v[44:45], v[48:49], v[52:53]
	v_cvt_pk_bf16_f32 v42, v42, v43
	v_cvt_pk_bf16_f32 v43, v44, v45
	global_store_dwordx2 v[32:33], v[42:43], off offset:1536 sc1
	v_pk_mul_f32 v[50:51], v[12:13], v[70:71] op_sel_hi:[1, 0]
	v_pk_mul_f32 v[52:53], v[14:15], v[70:71] op_sel_hi:[1, 0]
	ds_read_b128 v[12:15], v40 offset:12288
	ds_read_b128 v[46:49], v40 offset:4096
	s_waitcnt lgkmcnt(1)
	v_pk_add_f32 v[12:13], v[12:13], 1.0 op_sel_hi:[1, 0]
	v_pk_add_f32 v[14:15], v[14:15], 1.0 op_sel_hi:[1, 0]
	s_waitcnt vmcnt(4)
	v_pk_mul_f32 v[42:43], v[50:51], v[196:197]
	v_pk_mul_f32 v[44:45], v[52:53], v[198:199]
	s_waitcnt lgkmcnt(0)
	v_pk_fma_f32 v[12:13], v[42:43], v[12:13], v[46:47]
	v_pk_fma_f32 v[14:15], v[44:45], v[14:15], v[48:49]
	v_cvt_pk_bf16_f32 v12, v12, v13
	v_cvt_pk_bf16_f32 v13, v14, v15
	global_store_dwordx2 v[32:33], v[12:13], off offset:2048 sc1
	v_pk_mul_f32 v[46:47], v[8:9], v[70:71] op_sel_hi:[1, 0]
	v_pk_mul_f32 v[48:49], v[10:11], v[70:71] op_sel_hi:[1, 0]
	ds_read_b128 v[8:11], v40 offset:13312
	ds_read_b128 v[42:45], v40 offset:5120
	s_waitcnt lgkmcnt(1)
	v_pk_add_f32 v[8:9], v[8:9], 1.0 op_sel_hi:[1, 0]
	v_pk_add_f32 v[10:11], v[10:11], 1.0 op_sel_hi:[1, 0]
	s_waitcnt vmcnt(5)
	v_pk_mul_f32 v[12:13], v[46:47], v[200:201]
	v_pk_mul_f32 v[14:15], v[48:49], v[202:203]
	s_waitcnt lgkmcnt(0)
	v_pk_fma_f32 v[8:9], v[12:13], v[8:9], v[42:43]
	v_pk_fma_f32 v[10:11], v[14:15], v[10:11], v[44:45]
	v_cvt_pk_bf16_f32 v8, v8, v9
	v_cvt_pk_bf16_f32 v9, v10, v11
	global_store_dwordx2 v[32:33], v[8:9], off offset:2560 sc1
	v_pk_mul_f32 v[42:43], v[4:5], v[70:71] op_sel_hi:[1, 0]
	v_pk_mul_f32 v[44:45], v[6:7], v[70:71] op_sel_hi:[1, 0]
	ds_read_b128 v[4:7], v40 offset:14336
	ds_read_b128 v[12:15], v40 offset:6144
	s_waitcnt lgkmcnt(1)
	v_pk_add_f32 v[4:5], v[4:5], 1.0 op_sel_hi:[1, 0]
	v_pk_add_f32 v[6:7], v[6:7], 1.0 op_sel_hi:[1, 0]
	s_waitcnt vmcnt(6)
	v_pk_mul_f32 v[8:9], v[42:43], v[204:205]
	v_pk_mul_f32 v[10:11], v[44:45], v[206:207]
	s_waitcnt lgkmcnt(0)
	v_pk_fma_f32 v[4:5], v[8:9], v[4:5], v[12:13]
	v_pk_fma_f32 v[6:7], v[10:11], v[6:7], v[14:15]
	v_cvt_pk_bf16_f32 v4, v4, v5
	v_cvt_pk_bf16_f32 v5, v6, v7
	global_store_dwordx2 v[32:33], v[4:5], off offset:3072 sc1
	v_pk_mul_f32 v[12:13], v[0:1], v[70:71] op_sel_hi:[1, 0]
	v_pk_mul_f32 v[14:15], v[2:3], v[70:71] op_sel_hi:[1, 0]
	ds_read_b128 v[0:3], v40 offset:15360
	ds_read_b128 v[8:11], v40 offset:7168
	s_waitcnt lgkmcnt(1)
	v_pk_add_f32 v[0:1], v[0:1], 1.0 op_sel_hi:[1, 0]
	v_pk_add_f32 v[2:3], v[2:3], 1.0 op_sel_hi:[1, 0]
	s_waitcnt vmcnt(7)
	v_pk_mul_f32 v[4:5], v[12:13], v[208:209]
	v_pk_mul_f32 v[6:7], v[14:15], v[210:211]
	s_waitcnt lgkmcnt(0)
	v_pk_fma_f32 v[0:1], v[4:5], v[0:1], v[8:9]
	v_pk_fma_f32 v[2:3], v[6:7], v[2:3], v[10:11]
	v_cvt_pk_bf16_f32 v0, v0, v1
	v_cvt_pk_bf16_f32 v1, v2, v3
	global_store_dwordx2 v[32:33], v[0:1], off offset:3584 sc1
	s_cbranch_scc0 .LBB0_229
	s_waitcnt vmcnt(0)
	s_barrier
	s_and_saveexec_b64 s[0:1], s[4:5]
	s_cbranch_execz .LBB0_236
	s_lshl_b32 s2, s12, 2
	s_mov_b64 s[8:9], exec
	s_add_u32 s2, s22, s2
	s_addc_u32 s7, s23, 0
	v_mbcnt_lo_u32_b32 v0, s8, 0
	s_add_u32 s6, s2, 0x1be4c020
	v_mbcnt_hi_u32_b32 v0, s9, v0
	s_addc_u32 s7, s7, 0
	v_cmp_eq_u32_e32 vcc, 0, v0
	s_and_saveexec_b64 s[10:11], vcc
	s_cbranch_execz .LBB0_233
	s_bcnt1_i32_b64 s2, s[8:9]
	v_mov_b32_e32 v0, 0
	v_mov_b32_e32 v1, s2
	global_atomic_add v0, v1, s[6:7]
